# phase 0 wab table fill: one batch of 32 loads instead of four dependent rounds
# baseline (speedup 1.0000x reference)
.LBB0_164:
	s_waitcnt lgkmcnt(0)
	v_lshrrev_b32_e32 v100, 3, v8
	v_and_b32_e32 v101, 7, v8
	v_lshlrev_b32_e32 v102, 2, v100
	global_load_dword v104, v102, s[28:29]
	global_load_dword v105, v102, s[28:29] offset:256
	global_load_dword v106, v102, s[28:29] offset:512
	global_load_dword v107, v102, s[28:29] offset:768
	global_load_dword v108, v102, s[28:29] offset:1024
	global_load_dword v109, v102, s[28:29] offset:1280
	global_load_dword v110, v102, s[28:29] offset:1536
	global_load_dword v111, v102, s[28:29] offset:1792
	global_load_dword v112, v102, s[28:29] offset:2048
	global_load_dword v113, v102, s[28:29] offset:2304
	global_load_dword v114, v102, s[28:29] offset:2560
	global_load_dword v115, v102, s[28:29] offset:2816
	global_load_dword v116, v102, s[28:29] offset:3072
	global_load_dword v117, v102, s[28:29] offset:3328
	global_load_dword v118, v102, s[28:29] offset:3584
	global_load_dword v119, v102, s[28:29] offset:3840
	v_mul_u32_u24_e32 v120, 0x7820, v100
	v_lshl_add_u32 v120, v101, 2, v120
	v_add_u32_e32 v120, 0x4000, v120
	global_load_dword v124, v120, s[30:31]
	v_add_u32_e32 v120, 0x1e0800, v120
	global_load_dword v125, v120, s[30:31]
	v_add_u32_e32 v120, 0x1e0800, v120
	global_load_dword v126, v120, s[30:31]
	v_add_u32_e32 v120, 0x1e0800, v120
	global_load_dword v127, v120, s[30:31]
	v_add_u32_e32 v120, 0x1e0800, v120
	global_load_dword v128, v120, s[30:31]
	v_add_u32_e32 v120, 0x1e0800, v120
	global_load_dword v129, v120, s[30:31]
	v_add_u32_e32 v120, 0x1e0800, v120
	global_load_dword v130, v120, s[30:31]
	v_add_u32_e32 v120, 0x1e0800, v120
	global_load_dword v131, v120, s[30:31]
	v_add_u32_e32 v120, 0x1e0800, v120
	global_load_dword v132, v120, s[30:31]
	v_add_u32_e32 v120, 0x1e0800, v120
	global_load_dword v133, v120, s[30:31]
	v_add_u32_e32 v120, 0x1e0800, v120
	global_load_dword v134, v120, s[30:31]
	v_add_u32_e32 v120, 0x1e0800, v120
	global_load_dword v135, v120, s[30:31]
	v_add_u32_e32 v120, 0x1e0800, v120
	global_load_dword v136, v120, s[30:31]
	v_add_u32_e32 v120, 0x1e0800, v120
	global_load_dword v137, v120, s[30:31]
	v_add_u32_e32 v120, 0x1e0800, v120
	global_load_dword v138, v120, s[30:31]
	v_add_u32_e32 v120, 0x1e0800, v120
	global_load_dword v139, v120, s[30:31]
	v_lshlrev_b32_e32 v121, 2, v8
	s_waitcnt vmcnt(0)
	v_mul_f32_e32 v104, v104, v124
	v_mul_f32_e32 v105, v105, v125
	v_mul_f32_e32 v106, v106, v126
	v_mul_f32_e32 v107, v107, v127
	v_mul_f32_e32 v108, v108, v128
	v_mul_f32_e32 v109, v109, v129
	v_mul_f32_e32 v110, v110, v130
	v_mul_f32_e32 v111, v111, v131
	v_mul_f32_e32 v112, v112, v132
	v_mul_f32_e32 v113, v113, v133
	v_mul_f32_e32 v114, v114, v134
	v_mul_f32_e32 v115, v115, v135
	v_mul_f32_e32 v116, v116, v136
	v_mul_f32_e32 v117, v117, v137
	v_mul_f32_e32 v118, v118, v138
	v_mul_f32_e32 v119, v119, v139
	ds_write2st64_b32 v121, v104, v105 offset1:8
	ds_write2st64_b32 v121, v106, v107 offset0:16 offset1:24
	ds_write2st64_b32 v121, v108, v109 offset0:32 offset1:40
	ds_write2st64_b32 v121, v110, v111 offset0:48 offset1:56
	ds_write2st64_b32 v121, v112, v113 offset0:64 offset1:72
	ds_write2st64_b32 v121, v114, v115 offset0:80 offset1:88
	ds_write2st64_b32 v121, v116, v117 offset0:96 offset1:104
	ds_write2st64_b32 v121, v118, v119 offset0:112 offset1:120
